# dense-attn steady loop unrolled to 6 steps with static ring-slot offsets (no per-step address VALU / slot-rotation SALU)
# speedup vs baseline: 1.0246x; 1.0246x over previous
; #define WAIT_BAR(N) asm volatile("s_waitcnt vmcnt(" #N ") lgkmcnt(0)\n\ts_barrier":::"memory")
;   #define RESC() do{}while(0)
;   #define ROT() do{sl_prev=sl_cur;sl_cur=sl_next;sl_next=(sl_next==(NSLOT-1)*SLOTB)?0:sl_next+SLOTB;}while(0)
; template<int THRL> __device__ __forceinline__ void attn_unit(int b,int h,int qb,const bf16*Q,const bf16*__restrict__ K,const bf16*__restrict__ V,bf16*O,float*gssrow,float mref,char*shm){
;     ...
;   for(;t+5<NT;t+=2){
;     STEP(pB0,pB1,pA0,pA1,t,true,true,true);     WAIT_BAR(2); RESC(); ROT();
;     STEP(pA0,pA1,pB0,pB1,t+1,true,true,true);   WAIT_BAR(2); RESC(); ROT();
;   }
.Lattn6:
	ds_read_b64_tr_b16 v[204:205], v199 offset:24576
	ds_read_b64_tr_b16 v[206:207], v199 offset:25088
	v_add_f32_e32 v84, v64, v65
	v_add_f32_e32 v84, v66, v84
	v_add_f32_e32 v84, v67, v84
	v_add_f32_e32 v84, v68, v84
	v_add_f32_e32 v84, v69, v84
	v_cvt_pk_bf16_f32 v154, v64, v65
	v_cvt_pk_bf16_f32 v155, v66, v67
	v_mfma_f32_32x32x16_bf16 v[96:111], v[80:83], v[158:161], v[32:47]
	ds_read_b64_tr_b16 v[64:65], v199 offset:28672
	ds_read_b64_tr_b16 v[66:67], v199 offset:29184
	v_add_f32_e32 v80, v70, v84
	v_add_f32_e32 v80, v71, v80
	v_add_f32_e32 v80, v72, v80
	v_add_f32_e32 v130, v73, v80
	v_mfma_f32_32x32x16_bf16 v[80:95], v[166:169], v[158:161], v[32:47]
	v_cvt_pk_bf16_f32 v156, v68, v69
	v_cvt_pk_bf16_f32 v157, v70, v71
	ds_read_b64_tr_b16 v[68:69], v199 offset:25600
	ds_read_b64_tr_b16 v[70:71], v199 offset:26112
	v_add_f32_e32 v130, v74, v130
	v_add_f32_e32 v130, v75, v130
	v_add_f32_e32 v130, v76, v130
	v_add_f32_e32 v130, v77, v130
	v_cvt_pk_bf16_f32 v146, v72, v73
	v_cvt_pk_bf16_f32 v147, v74, v75
	v_mfma_f32_32x32x16_bf16 v[96:111], v[170:173], v[150:153], v[96:111]
	ds_read_b64_tr_b16 v[72:73], v199 offset:29696
	ds_read_b64_tr_b16 v[74:75], v199 offset:30208
	v_mfma_f32_32x32x16_bf16 v[80:95], v[162:165], v[150:153], v[80:95]
	v_add_f32_e32 v130, v78, v130
	v_add_f32_e32 v130, v79, v130
	v_add_f32_e32 v130, v48, v130
	v_add_f32_e32 v130, v49, v130
	v_cvt_pk_bf16_f32 v148, v76, v77
	v_cvt_pk_bf16_f32 v149, v78, v79
	ds_read_b64_tr_b16 v[76:77], v199 offset:26624
	ds_read_b64_tr_b16 v[78:79], v199 offset:27136
	v_mfma_f32_32x32x16_bf16 v[96:111], v[124:127], v[142:145], v[96:111]
	v_add_f32_e32 v124, v50, v130
	v_add_f32_e32 v124, v51, v124
	v_add_f32_e32 v124, v52, v124
	v_add_f32_e32 v124, v53, v124
	v_cvt_pk_bf16_f32 v138, v48, v49
	v_cvt_pk_bf16_f32 v139, v50, v51
	ds_read_b64_tr_b16 v[48:49], v199 offset:30720
	ds_read_b64_tr_b16 v[50:51], v199 offset:31232
	v_mfma_f32_32x32x16_bf16 v[80:95], v[120:123], v[142:145], v[80:95]
	v_add_f32_e32 v120, v54, v124
	v_add_f32_e32 v120, v55, v120
	v_add_f32_e32 v120, v56, v120
	v_add_f32_e32 v120, v57, v120
	v_cvt_pk_bf16_f32 v140, v52, v53
	v_cvt_pk_bf16_f32 v141, v54, v55
	ds_read_b64_tr_b16 v[52:53], v199 offset:27648
	ds_read_b64_tr_b16 v[54:55], v199 offset:28160
	v_mfma_f32_32x32x16_bf16 v[96:111], v[116:119], v[134:137], v[96:111]
	v_add_f32_e32 v116, v58, v120
	v_add_f32_e32 v116, v59, v116
	v_add_f32_e32 v116, v60, v116
	v_add_f32_e32 v116, v61, v116
	v_cvt_pk_bf16_f32 v130, v56, v57
	v_cvt_pk_bf16_f32 v131, v58, v59
	ds_read_b64_tr_b16 v[56:57], v199 offset:31744
	ds_read_b64_tr_b16 v[58:59], v199 offset:32256
	v_mfma_f32_32x32x16_bf16 v[80:95], v[112:115], v[134:137], v[80:95]
	v_add_f32_e32 v112, v62, v116
	v_add_f32_e32 v112, v63, v112
	v_cvt_pk_bf16_f32 v132, v60, v61
	v_cvt_pk_bf16_f32 v133, v62, v63
	s_add_i32 m0, s5, 0x2000
	s_nop 0
	global_load_lds_dwordx4 v216, s[98:99]
	s_add_i32 m0, s4, 0x4000
	s_nop 0
	global_load_lds_dwordx4 v217, s[100:101]
	v_add_f32_e32 v128, v203, v112
	s_waitcnt lgkmcnt(14)
	v_mfma_f32_32x32x16_bf16 v[0:15], v[154:157], v[204:207], v[0:15]
	v_exp_f32_e32 v96, v96
	v_exp_f32_e32 v97, v97
	v_exp_f32_e32 v98, v98
	v_exp_f32_e32 v99, v99
	s_waitcnt lgkmcnt(12)
	v_mfma_f32_32x32x16_bf16 v[16:31], v[154:157], v[64:67], v[16:31]
	v_exp_f32_e32 v100, v100
	v_exp_f32_e32 v101, v101
	v_exp_f32_e32 v102, v102
	v_exp_f32_e32 v103, v103
	ds_read_b128 v[60:63], v200 offset:16384
	ds_read_b128 v[116:119], v200 offset:16896
	s_waitcnt lgkmcnt(12)
	v_mfma_f32_32x32x16_bf16 v[0:15], v[146:149], v[68:71], v[0:15]
	v_exp_f32_e32 v104, v104
	v_exp_f32_e32 v105, v105
	v_exp_f32_e32 v106, v106
	v_exp_f32_e32 v107, v107
	ds_read_b128 v[120:123], v200 offset:18432
	ds_read_b128 v[124:127], v200 offset:18944
	s_waitcnt lgkmcnt(12)
	v_mfma_f32_32x32x16_bf16 v[16:31], v[146:149], v[72:75], v[16:31]
	v_exp_f32_e32 v108, v108
	v_exp_f32_e32 v109, v109
	v_exp_f32_e32 v110, v110
	v_exp_f32_e32 v111, v111
	ds_read_b128 v[162:165], v200 offset:20480
	ds_read_b128 v[166:169], v200 offset:20992
	s_waitcnt lgkmcnt(12)
	v_mfma_f32_32x32x16_bf16 v[0:15], v[138:141], v[76:79], v[0:15]
	v_exp_f32_e32 v80, v80
	v_exp_f32_e32 v81, v81
	v_exp_f32_e32 v82, v82
	v_exp_f32_e32 v83, v83
	ds_read_b128 v[170:173], v200 offset:22528
	ds_read_b128 v[112:115], v200 offset:23040
	s_waitcnt lgkmcnt(12)
	v_mfma_f32_32x32x16_bf16 v[16:31], v[138:141], v[48:51], v[16:31]
	v_exp_f32_e32 v84, v84
	v_exp_f32_e32 v85, v85
	v_exp_f32_e32 v86, v86
	v_exp_f32_e32 v87, v87
	s_waitcnt lgkmcnt(10)
	v_mfma_f32_32x32x16_bf16 v[0:15], v[130:133], v[52:55], v[0:15]
	v_exp_f32_e32 v88, v88
	v_exp_f32_e32 v89, v89
	v_exp_f32_e32 v90, v90
	v_exp_f32_e32 v91, v91
	s_waitcnt lgkmcnt(8)
	v_mfma_f32_32x32x16_bf16 v[16:31], v[130:133], v[56:59], v[16:31]
	v_exp_f32_e32 v92, v92
	v_exp_f32_e32 v93, v93
	v_exp_f32_e32 v94, v94
	v_exp_f32_e32 v95, v95
	s_waitcnt vmcnt(2) lgkmcnt(0)
	s_barrier
; #define WAIT_BAR(N) asm volatile("s_waitcnt vmcnt(" #N ") lgkmcnt(0)\n\ts_barrier":::"memory")
;   #define RESC() do{}while(0)
;   #define ROT() do{sl_prev=sl_cur;sl_cur=sl_next;sl_next=(sl_next==(NSLOT-1)*SLOTB)?0:sl_next+SLOTB;}while(0)
; template<int THRL> __device__ __forceinline__ void attn_unit(int b,int h,int qb,const bf16*Q,const bf16*__restrict__ K,const bf16*__restrict__ V,bf16*O,float*gssrow,float mref,char*shm){
;     ...
;   for(;t+5<NT;t+=2){
;     STEP(pB0,pB1,pA0,pA1,t,true,true,true);     WAIT_BAR(2); RESC(); ROT();
;     STEP(pA0,pA1,pB0,pB1,t+1,true,true,true);   WAIT_BAR(2); RESC(); ROT();
;   }
	ds_read_b64_tr_b16 v[204:205], v199 offset:32768
	ds_read_b64_tr_b16 v[206:207], v199 offset:33280
	v_mfma_f32_32x32x16_bf16 v[64:79], v[60:63], v[158:161], v[32:47]
	v_add_f32_e32 v48, v96, v97
	v_add_f32_e32 v48, v98, v48
	v_add_f32_e32 v48, v99, v48
	v_add_f32_e32 v48, v100, v48
	v_add_f32_e32 v48, v101, v48
	v_cvt_pk_bf16_f32 v154, v96, v97
	v_cvt_pk_bf16_f32 v155, v98, v99
	ds_read_b64_tr_b16 v[96:97], v199 offset:36864
	ds_read_b64_tr_b16 v[98:99], v199 offset:37376
	v_add_f32_e32 v48, v102, v48
	v_add_f32_e32 v48, v103, v48
	v_add_f32_e32 v48, v104, v48
	v_add_f32_e32 v130, v105, v48
	v_mfma_f32_32x32x16_bf16 v[48:63], v[116:119], v[158:161], v[32:47]
	v_cvt_pk_bf16_f32 v156, v100, v101
	v_cvt_pk_bf16_f32 v157, v102, v103
	ds_read_b64_tr_b16 v[100:101], v199 offset:33792
	ds_read_b64_tr_b16 v[102:103], v199 offset:34304
	v_mfma_f32_32x32x16_bf16 v[64:79], v[120:123], v[150:153], v[64:79]
	v_add_f32_e32 v116, v106, v130
	v_add_f32_e32 v116, v107, v116
	v_add_f32_e32 v116, v108, v116
	v_add_f32_e32 v116, v109, v116
	v_cvt_pk_bf16_f32 v146, v104, v105
	v_cvt_pk_bf16_f32 v147, v106, v107
	ds_read_b64_tr_b16 v[104:105], v199 offset:37888
	ds_read_b64_tr_b16 v[106:107], v199 offset:38400
	v_mfma_f32_32x32x16_bf16 v[48:63], v[124:127], v[150:153], v[48:63]
	v_add_f32_e32 v116, v110, v116
	v_add_f32_e32 v116, v111, v116
	v_add_f32_e32 v116, v80, v116
	v_add_f32_e32 v116, v81, v116
	v_cvt_pk_bf16_f32 v148, v108, v109
	v_cvt_pk_bf16_f32 v149, v110, v111
	ds_read_b64_tr_b16 v[108:109], v199 offset:34816
	ds_read_b64_tr_b16 v[110:111], v199 offset:35328
	v_mfma_f32_32x32x16_bf16 v[64:79], v[162:165], v[142:145], v[64:79]
	v_add_f32_e32 v116, v82, v116
	v_add_f32_e32 v116, v83, v116
	v_add_f32_e32 v116, v84, v116
	v_add_f32_e32 v116, v85, v116
	v_cvt_pk_bf16_f32 v138, v80, v81
	v_cvt_pk_bf16_f32 v139, v82, v83
	ds_read_b64_tr_b16 v[208:209], v199 offset:38912
	ds_read_b64_tr_b16 v[210:211], v199 offset:39424
	v_mfma_f32_32x32x16_bf16 v[48:63], v[166:169], v[142:145], v[48:63]
	v_add_f32_e32 v80, v86, v116
	v_add_f32_e32 v80, v87, v80
	v_add_f32_e32 v80, v88, v80
	v_add_f32_e32 v80, v89, v80
	v_cvt_pk_bf16_f32 v140, v84, v85
	v_cvt_pk_bf16_f32 v141, v86, v87
	ds_read_b64_tr_b16 v[84:85], v199 offset:35840
	ds_read_b64_tr_b16 v[86:87], v199 offset:36352
	v_mfma_f32_32x32x16_bf16 v[64:79], v[170:173], v[134:137], v[64:79]
	v_add_f32_e32 v80, v90, v80
	v_add_f32_e32 v80, v91, v80
	v_add_f32_e32 v80, v92, v80
	v_add_f32_e32 v80, v93, v80
	v_cvt_pk_bf16_f32 v130, v88, v89
	v_cvt_pk_bf16_f32 v131, v90, v91
	ds_read_b64_tr_b16 v[88:89], v199 offset:39936
	ds_read_b64_tr_b16 v[90:91], v199 offset:40448
	v_mfma_f32_32x32x16_bf16 v[48:63], v[112:115], v[134:137], v[48:63]
	v_add_f32_e32 v80, v94, v80
	v_add_f32_e32 v80, v95, v80
	v_cvt_pk_bf16_f32 v132, v92, v93
	v_cvt_pk_bf16_f32 v133, v94, v95
	v_add_f32_e32 v203, v128, v80
	s_add_i32 m0, s5, 0x4000
	s_nop 0
	global_load_lds_dwordx4 v218, s[98:99]
	s_mov_b32 m0, s4
	s_nop 0
	global_load_lds_dwordx4 v219, s[100:101]
	s_waitcnt lgkmcnt(14)
	v_mfma_f32_32x32x16_bf16 v[0:15], v[154:157], v[204:207], v[0:15]
	v_exp_f32_e32 v64, v64
	v_exp_f32_e32 v65, v65
	v_exp_f32_e32 v66, v66
	v_exp_f32_e32 v67, v67
	s_waitcnt lgkmcnt(12)
	v_mfma_f32_32x32x16_bf16 v[16:31], v[154:157], v[96:99], v[16:31]
	v_exp_f32_e32 v68, v68
	v_exp_f32_e32 v69, v69
	v_exp_f32_e32 v70, v70
	v_exp_f32_e32 v71, v71
	ds_read_b128 v[80:83], v200
	ds_read_b128 v[166:169], v200 offset:512
	s_waitcnt lgkmcnt(12)
	v_mfma_f32_32x32x16_bf16 v[0:15], v[146:149], v[100:103], v[0:15]
	v_exp_f32_e32 v72, v72
	v_exp_f32_e32 v73, v73
	v_exp_f32_e32 v74, v74
	v_exp_f32_e32 v75, v75
	ds_read_b128 v[170:173], v200 offset:2048
	ds_read_b128 v[162:165], v200 offset:2560
	s_waitcnt lgkmcnt(12)
	v_mfma_f32_32x32x16_bf16 v[16:31], v[146:149], v[104:107], v[16:31]
	v_exp_f32_e32 v76, v76
	v_exp_f32_e32 v77, v77
	v_exp_f32_e32 v78, v78
	v_exp_f32_e32 v79, v79
	ds_read_b128 v[124:127], v200 offset:4096
	ds_read_b128 v[120:123], v200 offset:4608
	s_waitcnt lgkmcnt(12)
	v_mfma_f32_32x32x16_bf16 v[0:15], v[138:141], v[108:111], v[0:15]
	v_exp_f32_e32 v48, v48
	v_exp_f32_e32 v49, v49
	v_exp_f32_e32 v50, v50
	v_exp_f32_e32 v51, v51
	ds_read_b128 v[116:119], v200 offset:6144
	ds_read_b128 v[112:115], v200 offset:6656
	s_waitcnt lgkmcnt(12)
	v_mfma_f32_32x32x16_bf16 v[16:31], v[138:141], v[208:211], v[16:31]
	v_exp_f32_e32 v52, v52
	v_exp_f32_e32 v53, v53
	v_exp_f32_e32 v54, v54
	v_exp_f32_e32 v55, v55
	s_waitcnt lgkmcnt(10)
	v_mfma_f32_32x32x16_bf16 v[0:15], v[130:133], v[84:87], v[0:15]
	v_exp_f32_e32 v56, v56
	v_exp_f32_e32 v57, v57
	v_exp_f32_e32 v58, v58
	v_exp_f32_e32 v59, v59
	s_waitcnt lgkmcnt(8)
	v_mfma_f32_32x32x16_bf16 v[16:31], v[130:133], v[88:91], v[16:31]
	v_exp_f32_e32 v60, v60
	v_exp_f32_e32 v61, v61
	v_exp_f32_e32 v62, v62
	v_exp_f32_e32 v63, v63
	s_waitcnt vmcnt(2) lgkmcnt(0)
	s_barrier
; #define WAIT_BAR(N) asm volatile("s_waitcnt vmcnt(" #N ") lgkmcnt(0)\n\ts_barrier":::"memory")
;   #define RESC() do{}while(0)
;   #define ROT() do{sl_prev=sl_cur;sl_cur=sl_next;sl_next=(sl_next==(NSLOT-1)*SLOTB)?0:sl_next+SLOTB;}while(0)
; template<int THRL> __device__ __forceinline__ void attn_unit(int b,int h,int qb,const bf16*Q,const bf16*__restrict__ K,const bf16*__restrict__ V,bf16*O,float*gssrow,float mref,char*shm){
;     ...
;   for(;t+5<NT;t+=2){
;     STEP(pB0,pB1,pA0,pA1,t,true,true,true);     WAIT_BAR(2); RESC(); ROT();
;     STEP(pA0,pA1,pB0,pB1,t+1,true,true,true);   WAIT_BAR(2); RESC(); ROT();
;   }
	s_add_u32 s98, s98, 0x8000
	s_addc_u32 s99, s99, 0
	s_add_u32 s100, s100, 0x8000
	s_addc_u32 s101, s101, 0
	ds_read_b64_tr_b16 v[204:205], v199 offset:40960
	ds_read_b64_tr_b16 v[206:207], v199 offset:41472
	v_add_f32_e32 v84, v64, v65
	v_add_f32_e32 v84, v66, v84
	v_add_f32_e32 v84, v67, v84
	v_add_f32_e32 v84, v68, v84
	v_add_f32_e32 v84, v69, v84
	v_cvt_pk_bf16_f32 v154, v64, v65
	v_cvt_pk_bf16_f32 v155, v66, v67
	v_mfma_f32_32x32x16_bf16 v[96:111], v[80:83], v[158:161], v[32:47]
	ds_read_b64_tr_b16 v[64:65], v199 offset:45056
	ds_read_b64_tr_b16 v[66:67], v199 offset:45568
	v_add_f32_e32 v80, v70, v84
	v_add_f32_e32 v80, v71, v80
	v_add_f32_e32 v80, v72, v80
	v_add_f32_e32 v130, v73, v80
	v_mfma_f32_32x32x16_bf16 v[80:95], v[166:169], v[158:161], v[32:47]
	v_cvt_pk_bf16_f32 v156, v68, v69
	v_cvt_pk_bf16_f32 v157, v70, v71
	ds_read_b64_tr_b16 v[68:69], v199 offset:41984
	ds_read_b64_tr_b16 v[70:71], v199 offset:42496
	v_add_f32_e32 v130, v74, v130
	v_add_f32_e32 v130, v75, v130
	v_add_f32_e32 v130, v76, v130
	v_add_f32_e32 v130, v77, v130
	v_cvt_pk_bf16_f32 v146, v72, v73
	v_cvt_pk_bf16_f32 v147, v74, v75
	v_mfma_f32_32x32x16_bf16 v[96:111], v[170:173], v[150:153], v[96:111]
	ds_read_b64_tr_b16 v[72:73], v199 offset:46080
	ds_read_b64_tr_b16 v[74:75], v199 offset:46592
	v_mfma_f32_32x32x16_bf16 v[80:95], v[162:165], v[150:153], v[80:95]
	v_add_f32_e32 v130, v78, v130
	v_add_f32_e32 v130, v79, v130
	v_add_f32_e32 v130, v48, v130
	v_add_f32_e32 v130, v49, v130
	v_cvt_pk_bf16_f32 v148, v76, v77
	v_cvt_pk_bf16_f32 v149, v78, v79
	ds_read_b64_tr_b16 v[76:77], v199 offset:43008
	ds_read_b64_tr_b16 v[78:79], v199 offset:43520
	v_mfma_f32_32x32x16_bf16 v[96:111], v[124:127], v[142:145], v[96:111]
	v_add_f32_e32 v124, v50, v130
	v_add_f32_e32 v124, v51, v124
	v_add_f32_e32 v124, v52, v124
	v_add_f32_e32 v124, v53, v124
	v_cvt_pk_bf16_f32 v138, v48, v49
	v_cvt_pk_bf16_f32 v139, v50, v51
	ds_read_b64_tr_b16 v[48:49], v199 offset:47104
	ds_read_b64_tr_b16 v[50:51], v199 offset:47616
	v_mfma_f32_32x32x16_bf16 v[80:95], v[120:123], v[142:145], v[80:95]
	v_add_f32_e32 v120, v54, v124
	v_add_f32_e32 v120, v55, v120
	v_add_f32_e32 v120, v56, v120
	v_add_f32_e32 v120, v57, v120
	v_cvt_pk_bf16_f32 v140, v52, v53
	v_cvt_pk_bf16_f32 v141, v54, v55
	ds_read_b64_tr_b16 v[52:53], v199 offset:44032
	ds_read_b64_tr_b16 v[54:55], v199 offset:44544
	v_mfma_f32_32x32x16_bf16 v[96:111], v[116:119], v[134:137], v[96:111]
	v_add_f32_e32 v116, v58, v120
	v_add_f32_e32 v116, v59, v116
	v_add_f32_e32 v116, v60, v116
	v_add_f32_e32 v116, v61, v116
	v_cvt_pk_bf16_f32 v130, v56, v57
	v_cvt_pk_bf16_f32 v131, v58, v59
	ds_read_b64_tr_b16 v[56:57], v199 offset:48128
	ds_read_b64_tr_b16 v[58:59], v199 offset:48640
	v_mfma_f32_32x32x16_bf16 v[80:95], v[112:115], v[134:137], v[80:95]
	v_add_f32_e32 v112, v62, v116
	v_add_f32_e32 v112, v63, v112
	v_cvt_pk_bf16_f32 v132, v60, v61
	v_cvt_pk_bf16_f32 v133, v62, v63
	s_mov_b32 m0, s5
	s_nop 0
	global_load_lds_dwordx4 v216, s[98:99]
	s_add_i32 m0, s4, 0x2000
	s_nop 0
	global_load_lds_dwordx4 v217, s[100:101]
	v_add_f32_e32 v128, v203, v112
	s_waitcnt lgkmcnt(14)
	v_mfma_f32_32x32x16_bf16 v[0:15], v[154:157], v[204:207], v[0:15]
	v_exp_f32_e32 v96, v96
	v_exp_f32_e32 v97, v97
	v_exp_f32_e32 v98, v98
	v_exp_f32_e32 v99, v99
	s_waitcnt lgkmcnt(12)
	v_mfma_f32_32x32x16_bf16 v[16:31], v[154:157], v[64:67], v[16:31]
	v_exp_f32_e32 v100, v100
	v_exp_f32_e32 v101, v101
	v_exp_f32_e32 v102, v102
	v_exp_f32_e32 v103, v103
	ds_read_b128 v[60:63], v200 offset:8192
	ds_read_b128 v[116:119], v200 offset:8704
	s_waitcnt lgkmcnt(12)
	v_mfma_f32_32x32x16_bf16 v[0:15], v[146:149], v[68:71], v[0:15]
	v_exp_f32_e32 v104, v104
	v_exp_f32_e32 v105, v105
	v_exp_f32_e32 v106, v106
	v_exp_f32_e32 v107, v107
	ds_read_b128 v[120:123], v200 offset:10240
	ds_read_b128 v[124:127], v200 offset:10752
	s_waitcnt lgkmcnt(12)
	v_mfma_f32_32x32x16_bf16 v[16:31], v[146:149], v[72:75], v[16:31]
	v_exp_f32_e32 v108, v108
	v_exp_f32_e32 v109, v109
	v_exp_f32_e32 v110, v110
	v_exp_f32_e32 v111, v111
	ds_read_b128 v[162:165], v200 offset:12288
	ds_read_b128 v[166:169], v200 offset:12800
	s_waitcnt lgkmcnt(12)
	v_mfma_f32_32x32x16_bf16 v[0:15], v[138:141], v[76:79], v[0:15]
	v_exp_f32_e32 v80, v80
	v_exp_f32_e32 v81, v81
	v_exp_f32_e32 v82, v82
	v_exp_f32_e32 v83, v83
	ds_read_b128 v[170:173], v200 offset:14336
	ds_read_b128 v[112:115], v200 offset:14848
	s_waitcnt lgkmcnt(12)
	v_mfma_f32_32x32x16_bf16 v[16:31], v[138:141], v[48:51], v[16:31]
	v_exp_f32_e32 v84, v84
	v_exp_f32_e32 v85, v85
	v_exp_f32_e32 v86, v86
	v_exp_f32_e32 v87, v87
	s_waitcnt lgkmcnt(10)
	v_mfma_f32_32x32x16_bf16 v[0:15], v[130:133], v[52:55], v[0:15]
	v_exp_f32_e32 v88, v88
	v_exp_f32_e32 v89, v89
	v_exp_f32_e32 v90, v90
	v_exp_f32_e32 v91, v91
	s_waitcnt lgkmcnt(8)
	v_mfma_f32_32x32x16_bf16 v[16:31], v[130:133], v[56:59], v[16:31]
	v_exp_f32_e32 v92, v92
	v_exp_f32_e32 v93, v93
	v_exp_f32_e32 v94, v94
	v_exp_f32_e32 v95, v95
	s_waitcnt vmcnt(2) lgkmcnt(0)
	s_barrier
; #define WAIT_BAR(N) asm volatile("s_waitcnt vmcnt(" #N ") lgkmcnt(0)\n\ts_barrier":::"memory")
;   #define RESC() do{}while(0)
;   #define ROT() do{sl_prev=sl_cur;sl_cur=sl_next;sl_next=(sl_next==(NSLOT-1)*SLOTB)?0:sl_next+SLOTB;}while(0)
; template<int THRL> __device__ __forceinline__ void attn_unit(int b,int h,int qb,const bf16*Q,const bf16*__restrict__ K,const bf16*__restrict__ V,bf16*O,float*gssrow,float mref,char*shm){
;     ...
;   for(;t+5<NT;t+=2){
;     STEP(pB0,pB1,pA0,pA1,t,true,true,true);     WAIT_BAR(2); RESC(); ROT();
;     STEP(pA0,pA1,pB0,pB1,t+1,true,true,true);   WAIT_BAR(2); RESC(); ROT();
;   }
	ds_read_b64_tr_b16 v[204:205], v199 offset:24576
	ds_read_b64_tr_b16 v[206:207], v199 offset:25088
	v_mfma_f32_32x32x16_bf16 v[64:79], v[60:63], v[158:161], v[32:47]
	v_add_f32_e32 v48, v96, v97
	v_add_f32_e32 v48, v98, v48
	v_add_f32_e32 v48, v99, v48
	v_add_f32_e32 v48, v100, v48
	v_add_f32_e32 v48, v101, v48
	v_cvt_pk_bf16_f32 v154, v96, v97
	v_cvt_pk_bf16_f32 v155, v98, v99
	ds_read_b64_tr_b16 v[96:97], v199 offset:28672
	ds_read_b64_tr_b16 v[98:99], v199 offset:29184
	v_add_f32_e32 v48, v102, v48
	v_add_f32_e32 v48, v103, v48
	v_add_f32_e32 v48, v104, v48
	v_add_f32_e32 v130, v105, v48
	v_mfma_f32_32x32x16_bf16 v[48:63], v[116:119], v[158:161], v[32:47]
	v_cvt_pk_bf16_f32 v156, v100, v101
	v_cvt_pk_bf16_f32 v157, v102, v103
	ds_read_b64_tr_b16 v[100:101], v199 offset:25600
	ds_read_b64_tr_b16 v[102:103], v199 offset:26112
	v_mfma_f32_32x32x16_bf16 v[64:79], v[120:123], v[150:153], v[64:79]
	v_add_f32_e32 v116, v106, v130
	v_add_f32_e32 v116, v107, v116
	v_add_f32_e32 v116, v108, v116
	v_add_f32_e32 v116, v109, v116
	v_cvt_pk_bf16_f32 v146, v104, v105
	v_cvt_pk_bf16_f32 v147, v106, v107
	ds_read_b64_tr_b16 v[104:105], v199 offset:29696
	ds_read_b64_tr_b16 v[106:107], v199 offset:30208
	v_mfma_f32_32x32x16_bf16 v[48:63], v[124:127], v[150:153], v[48:63]
	v_add_f32_e32 v116, v110, v116
	v_add_f32_e32 v116, v111, v116
	v_add_f32_e32 v116, v80, v116
	v_add_f32_e32 v116, v81, v116
	v_cvt_pk_bf16_f32 v148, v108, v109
	v_cvt_pk_bf16_f32 v149, v110, v111
	ds_read_b64_tr_b16 v[108:109], v199 offset:26624
	ds_read_b64_tr_b16 v[110:111], v199 offset:27136
	v_mfma_f32_32x32x16_bf16 v[64:79], v[162:165], v[142:145], v[64:79]
	v_add_f32_e32 v116, v82, v116
	v_add_f32_e32 v116, v83, v116
	v_add_f32_e32 v116, v84, v116
	v_add_f32_e32 v116, v85, v116
	v_cvt_pk_bf16_f32 v138, v80, v81
	v_cvt_pk_bf16_f32 v139, v82, v83
	ds_read_b64_tr_b16 v[208:209], v199 offset:30720
	ds_read_b64_tr_b16 v[210:211], v199 offset:31232
	v_mfma_f32_32x32x16_bf16 v[48:63], v[166:169], v[142:145], v[48:63]
	v_add_f32_e32 v80, v86, v116
	v_add_f32_e32 v80, v87, v80
	v_add_f32_e32 v80, v88, v80
	v_add_f32_e32 v80, v89, v80
	v_cvt_pk_bf16_f32 v140, v84, v85
	v_cvt_pk_bf16_f32 v141, v86, v87
	ds_read_b64_tr_b16 v[84:85], v199 offset:27648
	ds_read_b64_tr_b16 v[86:87], v199 offset:28160
	v_mfma_f32_32x32x16_bf16 v[64:79], v[170:173], v[134:137], v[64:79]
	v_add_f32_e32 v80, v90, v80
	v_add_f32_e32 v80, v91, v80
	v_add_f32_e32 v80, v92, v80
	v_add_f32_e32 v80, v93, v80
	v_cvt_pk_bf16_f32 v130, v88, v89
	v_cvt_pk_bf16_f32 v131, v90, v91
	ds_read_b64_tr_b16 v[88:89], v199 offset:31744
	ds_read_b64_tr_b16 v[90:91], v199 offset:32256
	v_mfma_f32_32x32x16_bf16 v[48:63], v[112:115], v[134:137], v[48:63]
	v_add_f32_e32 v80, v94, v80
	v_add_f32_e32 v80, v95, v80
	v_cvt_pk_bf16_f32 v132, v92, v93
	v_cvt_pk_bf16_f32 v133, v94, v95
	v_add_f32_e32 v203, v128, v80
	s_add_i32 m0, s5, 0x2000
	s_nop 0
	global_load_lds_dwordx4 v218, s[98:99]
	s_add_i32 m0, s4, 0x4000
	s_nop 0
	global_load_lds_dwordx4 v219, s[100:101]
	s_waitcnt lgkmcnt(14)
	v_mfma_f32_32x32x16_bf16 v[0:15], v[154:157], v[204:207], v[0:15]
	v_exp_f32_e32 v64, v64
	v_exp_f32_e32 v65, v65
	v_exp_f32_e32 v66, v66
	v_exp_f32_e32 v67, v67
	s_waitcnt lgkmcnt(12)
	v_mfma_f32_32x32x16_bf16 v[16:31], v[154:157], v[96:99], v[16:31]
	v_exp_f32_e32 v68, v68
	v_exp_f32_e32 v69, v69
	v_exp_f32_e32 v70, v70
	v_exp_f32_e32 v71, v71
	ds_read_b128 v[80:83], v200 offset:16384
	ds_read_b128 v[166:169], v200 offset:16896
	s_waitcnt lgkmcnt(12)
	v_mfma_f32_32x32x16_bf16 v[0:15], v[146:149], v[100:103], v[0:15]
	v_exp_f32_e32 v72, v72
	v_exp_f32_e32 v73, v73
	v_exp_f32_e32 v74, v74
	v_exp_f32_e32 v75, v75
	ds_read_b128 v[170:173], v200 offset:18432
	ds_read_b128 v[162:165], v200 offset:18944
	s_waitcnt lgkmcnt(12)
	v_mfma_f32_32x32x16_bf16 v[16:31], v[146:149], v[104:107], v[16:31]
	v_exp_f32_e32 v76, v76
	v_exp_f32_e32 v77, v77
	v_exp_f32_e32 v78, v78
	v_exp_f32_e32 v79, v79
	ds_read_b128 v[124:127], v200 offset:20480
	ds_read_b128 v[120:123], v200 offset:20992
	s_waitcnt lgkmcnt(12)
	v_mfma_f32_32x32x16_bf16 v[0:15], v[138:141], v[108:111], v[0:15]
	v_exp_f32_e32 v48, v48
	v_exp_f32_e32 v49, v49
	v_exp_f32_e32 v50, v50
	v_exp_f32_e32 v51, v51
	ds_read_b128 v[116:119], v200 offset:22528
	ds_read_b128 v[112:115], v200 offset:23040
	s_waitcnt lgkmcnt(12)
	v_mfma_f32_32x32x16_bf16 v[16:31], v[138:141], v[208:211], v[16:31]
	v_exp_f32_e32 v52, v52
	v_exp_f32_e32 v53, v53
	v_exp_f32_e32 v54, v54
	v_exp_f32_e32 v55, v55
	s_waitcnt lgkmcnt(10)
	v_mfma_f32_32x32x16_bf16 v[0:15], v[130:133], v[84:87], v[0:15]
	v_exp_f32_e32 v56, v56
	v_exp_f32_e32 v57, v57
	v_exp_f32_e32 v58, v58
	v_exp_f32_e32 v59, v59
	s_waitcnt lgkmcnt(8)
	v_mfma_f32_32x32x16_bf16 v[16:31], v[130:133], v[88:91], v[16:31]
	v_exp_f32_e32 v60, v60
	v_exp_f32_e32 v61, v61
	v_exp_f32_e32 v62, v62
	v_exp_f32_e32 v63, v63
	s_waitcnt vmcnt(2) lgkmcnt(0)
	s_barrier
; #define WAIT_BAR(N) asm volatile("s_waitcnt vmcnt(" #N ") lgkmcnt(0)\n\ts_barrier":::"memory")
;   #define RESC() do{}while(0)
;   #define ROT() do{sl_prev=sl_cur;sl_cur=sl_next;sl_next=(sl_next==(NSLOT-1)*SLOTB)?0:sl_next+SLOTB;}while(0)
; template<int THRL> __device__ __forceinline__ void attn_unit(int b,int h,int qb,const bf16*Q,const bf16*__restrict__ K,const bf16*__restrict__ V,bf16*O,float*gssrow,float mref,char*shm){
;     ...
;   for(;t+5<NT;t+=2){
;     STEP(pB0,pB1,pA0,pA1,t,true,true,true);     WAIT_BAR(2); RESC(); ROT();
;     STEP(pA0,pA1,pB0,pB1,t+1,true,true,true);   WAIT_BAR(2); RESC(); ROT();
;   }
	s_add_u32 s98, s98, 0x8000
	s_addc_u32 s99, s99, 0
	s_add_u32 s100, s100, 0x8000
	s_addc_u32 s101, s101, 0
	ds_read_b64_tr_b16 v[204:205], v199 offset:32768
	ds_read_b64_tr_b16 v[206:207], v199 offset:33280
	v_add_f32_e32 v84, v64, v65
	v_add_f32_e32 v84, v66, v84
	v_add_f32_e32 v84, v67, v84
	v_add_f32_e32 v84, v68, v84
	v_add_f32_e32 v84, v69, v84
	v_cvt_pk_bf16_f32 v154, v64, v65
	v_cvt_pk_bf16_f32 v155, v66, v67
	v_mfma_f32_32x32x16_bf16 v[96:111], v[80:83], v[158:161], v[32:47]
	ds_read_b64_tr_b16 v[64:65], v199 offset:36864
	ds_read_b64_tr_b16 v[66:67], v199 offset:37376
	v_add_f32_e32 v80, v70, v84
	v_add_f32_e32 v80, v71, v80
	v_add_f32_e32 v80, v72, v80
	v_add_f32_e32 v130, v73, v80
	v_mfma_f32_32x32x16_bf16 v[80:95], v[166:169], v[158:161], v[32:47]
	v_cvt_pk_bf16_f32 v156, v68, v69
	v_cvt_pk_bf16_f32 v157, v70, v71
	ds_read_b64_tr_b16 v[68:69], v199 offset:33792
	ds_read_b64_tr_b16 v[70:71], v199 offset:34304
	v_add_f32_e32 v130, v74, v130
	v_add_f32_e32 v130, v75, v130
	v_add_f32_e32 v130, v76, v130
	v_add_f32_e32 v130, v77, v130
	v_cvt_pk_bf16_f32 v146, v72, v73
	v_cvt_pk_bf16_f32 v147, v74, v75
	v_mfma_f32_32x32x16_bf16 v[96:111], v[170:173], v[150:153], v[96:111]
	ds_read_b64_tr_b16 v[72:73], v199 offset:37888
	ds_read_b64_tr_b16 v[74:75], v199 offset:38400
	v_mfma_f32_32x32x16_bf16 v[80:95], v[162:165], v[150:153], v[80:95]
	v_add_f32_e32 v130, v78, v130
	v_add_f32_e32 v130, v79, v130
	v_add_f32_e32 v130, v48, v130
	v_add_f32_e32 v130, v49, v130
	v_cvt_pk_bf16_f32 v148, v76, v77
	v_cvt_pk_bf16_f32 v149, v78, v79
	ds_read_b64_tr_b16 v[76:77], v199 offset:34816
	ds_read_b64_tr_b16 v[78:79], v199 offset:35328
	v_mfma_f32_32x32x16_bf16 v[96:111], v[124:127], v[142:145], v[96:111]
	v_add_f32_e32 v124, v50, v130
	v_add_f32_e32 v124, v51, v124
	v_add_f32_e32 v124, v52, v124
	v_add_f32_e32 v124, v53, v124
	v_cvt_pk_bf16_f32 v138, v48, v49
	v_cvt_pk_bf16_f32 v139, v50, v51
	ds_read_b64_tr_b16 v[48:49], v199 offset:38912
	ds_read_b64_tr_b16 v[50:51], v199 offset:39424
	v_mfma_f32_32x32x16_bf16 v[80:95], v[120:123], v[142:145], v[80:95]
	v_add_f32_e32 v120, v54, v124
	v_add_f32_e32 v120, v55, v120
	v_add_f32_e32 v120, v56, v120
	v_add_f32_e32 v120, v57, v120
	v_cvt_pk_bf16_f32 v140, v52, v53
	v_cvt_pk_bf16_f32 v141, v54, v55
	ds_read_b64_tr_b16 v[52:53], v199 offset:35840
	ds_read_b64_tr_b16 v[54:55], v199 offset:36352
	v_mfma_f32_32x32x16_bf16 v[96:111], v[116:119], v[134:137], v[96:111]
	v_add_f32_e32 v116, v58, v120
	v_add_f32_e32 v116, v59, v116
	v_add_f32_e32 v116, v60, v116
	v_add_f32_e32 v116, v61, v116
	v_cvt_pk_bf16_f32 v130, v56, v57
	v_cvt_pk_bf16_f32 v131, v58, v59
	ds_read_b64_tr_b16 v[56:57], v199 offset:39936
	ds_read_b64_tr_b16 v[58:59], v199 offset:40448
	v_mfma_f32_32x32x16_bf16 v[80:95], v[112:115], v[134:137], v[80:95]
	v_add_f32_e32 v112, v62, v116
	v_add_f32_e32 v112, v63, v112
	v_cvt_pk_bf16_f32 v132, v60, v61
	v_cvt_pk_bf16_f32 v133, v62, v63
	s_add_i32 m0, s5, 0x4000
	s_nop 0
	global_load_lds_dwordx4 v216, s[98:99]
	s_mov_b32 m0, s4
	s_nop 0
	global_load_lds_dwordx4 v217, s[100:101]
	v_add_f32_e32 v128, v203, v112
	s_waitcnt lgkmcnt(14)
	v_mfma_f32_32x32x16_bf16 v[0:15], v[154:157], v[204:207], v[0:15]
	v_exp_f32_e32 v96, v96
	v_exp_f32_e32 v97, v97
	v_exp_f32_e32 v98, v98
	v_exp_f32_e32 v99, v99
	s_waitcnt lgkmcnt(12)
	v_mfma_f32_32x32x16_bf16 v[16:31], v[154:157], v[64:67], v[16:31]
	v_exp_f32_e32 v100, v100
	v_exp_f32_e32 v101, v101
	v_exp_f32_e32 v102, v102
	v_exp_f32_e32 v103, v103
	ds_read_b128 v[60:63], v200
	ds_read_b128 v[116:119], v200 offset:512
	s_waitcnt lgkmcnt(12)
	v_mfma_f32_32x32x16_bf16 v[0:15], v[146:149], v[68:71], v[0:15]
	v_exp_f32_e32 v104, v104
	v_exp_f32_e32 v105, v105
	v_exp_f32_e32 v106, v106
	v_exp_f32_e32 v107, v107
	ds_read_b128 v[120:123], v200 offset:2048
	ds_read_b128 v[124:127], v200 offset:2560
	s_waitcnt lgkmcnt(12)
	v_mfma_f32_32x32x16_bf16 v[16:31], v[146:149], v[72:75], v[16:31]
	v_exp_f32_e32 v108, v108
	v_exp_f32_e32 v109, v109
	v_exp_f32_e32 v110, v110
	v_exp_f32_e32 v111, v111
	ds_read_b128 v[162:165], v200 offset:4096
	ds_read_b128 v[166:169], v200 offset:4608
	s_waitcnt lgkmcnt(12)
	v_mfma_f32_32x32x16_bf16 v[0:15], v[138:141], v[76:79], v[0:15]
	v_exp_f32_e32 v80, v80
	v_exp_f32_e32 v81, v81
	v_exp_f32_e32 v82, v82
	v_exp_f32_e32 v83, v83
	ds_read_b128 v[170:173], v200 offset:6144
	ds_read_b128 v[112:115], v200 offset:6656
	s_waitcnt lgkmcnt(12)
	v_mfma_f32_32x32x16_bf16 v[16:31], v[138:141], v[48:51], v[16:31]
	v_exp_f32_e32 v84, v84
	v_exp_f32_e32 v85, v85
	v_exp_f32_e32 v86, v86
	v_exp_f32_e32 v87, v87
	s_waitcnt lgkmcnt(10)
	v_mfma_f32_32x32x16_bf16 v[0:15], v[130:133], v[52:55], v[0:15]
	v_exp_f32_e32 v88, v88
	v_exp_f32_e32 v89, v89
	v_exp_f32_e32 v90, v90
	v_exp_f32_e32 v91, v91
	s_waitcnt lgkmcnt(8)
	v_mfma_f32_32x32x16_bf16 v[16:31], v[130:133], v[56:59], v[16:31]
	v_exp_f32_e32 v92, v92
	v_exp_f32_e32 v93, v93
	v_exp_f32_e32 v94, v94
	v_exp_f32_e32 v95, v95
	s_waitcnt vmcnt(2) lgkmcnt(0)
	s_barrier
; #define WAIT_BAR(N) asm volatile("s_waitcnt vmcnt(" #N ") lgkmcnt(0)\n\ts_barrier":::"memory")
;   #define RESC() do{}while(0)
;   #define ROT() do{sl_prev=sl_cur;sl_cur=sl_next;sl_next=(sl_next==(NSLOT-1)*SLOTB)?0:sl_next+SLOTB;}while(0)
; template<int THRL> __device__ __forceinline__ void attn_unit(int b,int h,int qb,const bf16*Q,const bf16*__restrict__ K,const bf16*__restrict__ V,bf16*O,float*gssrow,float mref,char*shm){
;     ...
;   for(;t+5<NT;t+=2){
;     STEP(pB0,pB1,pA0,pA1,t,true,true,true);     WAIT_BAR(2); RESC(); ROT();
;     STEP(pA0,pA1,pB0,pB1,t+1,true,true,true);   WAIT_BAR(2); RESC(); ROT();
;   }
	ds_read_b64_tr_b16 v[204:205], v199 offset:40960
	ds_read_b64_tr_b16 v[206:207], v199 offset:41472
	v_mfma_f32_32x32x16_bf16 v[64:79], v[60:63], v[158:161], v[32:47]
	v_add_f32_e32 v48, v96, v97
	v_add_f32_e32 v48, v98, v48
	v_add_f32_e32 v48, v99, v48
	v_add_f32_e32 v48, v100, v48
	v_add_f32_e32 v48, v101, v48
	v_cvt_pk_bf16_f32 v154, v96, v97
	v_cvt_pk_bf16_f32 v155, v98, v99
	ds_read_b64_tr_b16 v[96:97], v199 offset:45056
	ds_read_b64_tr_b16 v[98:99], v199 offset:45568
	v_add_f32_e32 v48, v102, v48
	v_add_f32_e32 v48, v103, v48
	v_add_f32_e32 v48, v104, v48
	v_add_f32_e32 v130, v105, v48
	v_mfma_f32_32x32x16_bf16 v[48:63], v[116:119], v[158:161], v[32:47]
	v_cvt_pk_bf16_f32 v156, v100, v101
	v_cvt_pk_bf16_f32 v157, v102, v103
	ds_read_b64_tr_b16 v[100:101], v199 offset:41984
	ds_read_b64_tr_b16 v[102:103], v199 offset:42496
	v_mfma_f32_32x32x16_bf16 v[64:79], v[120:123], v[150:153], v[64:79]
	v_add_f32_e32 v116, v106, v130
	v_add_f32_e32 v116, v107, v116
	v_add_f32_e32 v116, v108, v116
	v_add_f32_e32 v116, v109, v116
	v_cvt_pk_bf16_f32 v146, v104, v105
	v_cvt_pk_bf16_f32 v147, v106, v107
	ds_read_b64_tr_b16 v[104:105], v199 offset:46080
	ds_read_b64_tr_b16 v[106:107], v199 offset:46592
	v_mfma_f32_32x32x16_bf16 v[48:63], v[124:127], v[150:153], v[48:63]
	v_add_f32_e32 v116, v110, v116
	v_add_f32_e32 v116, v111, v116
	v_add_f32_e32 v116, v80, v116
	v_add_f32_e32 v116, v81, v116
	v_cvt_pk_bf16_f32 v148, v108, v109
	v_cvt_pk_bf16_f32 v149, v110, v111
	ds_read_b64_tr_b16 v[108:109], v199 offset:43008
	ds_read_b64_tr_b16 v[110:111], v199 offset:43520
	v_mfma_f32_32x32x16_bf16 v[64:79], v[162:165], v[142:145], v[64:79]
	v_add_f32_e32 v116, v82, v116
	v_add_f32_e32 v116, v83, v116
	v_add_f32_e32 v116, v84, v116
	v_add_f32_e32 v116, v85, v116
	v_cvt_pk_bf16_f32 v138, v80, v81
	v_cvt_pk_bf16_f32 v139, v82, v83
	ds_read_b64_tr_b16 v[208:209], v199 offset:47104
	ds_read_b64_tr_b16 v[210:211], v199 offset:47616
	v_mfma_f32_32x32x16_bf16 v[48:63], v[166:169], v[142:145], v[48:63]
	v_add_f32_e32 v80, v86, v116
	v_add_f32_e32 v80, v87, v80
	v_add_f32_e32 v80, v88, v80
	v_add_f32_e32 v80, v89, v80
	v_cvt_pk_bf16_f32 v140, v84, v85
	v_cvt_pk_bf16_f32 v141, v86, v87
	ds_read_b64_tr_b16 v[84:85], v199 offset:44032
	ds_read_b64_tr_b16 v[86:87], v199 offset:44544
	v_mfma_f32_32x32x16_bf16 v[64:79], v[170:173], v[134:137], v[64:79]
	v_add_f32_e32 v80, v90, v80
	v_add_f32_e32 v80, v91, v80
	v_add_f32_e32 v80, v92, v80
	v_add_f32_e32 v80, v93, v80
	v_cvt_pk_bf16_f32 v130, v88, v89
	v_cvt_pk_bf16_f32 v131, v90, v91
	ds_read_b64_tr_b16 v[88:89], v199 offset:48128
	ds_read_b64_tr_b16 v[90:91], v199 offset:48640
	v_mfma_f32_32x32x16_bf16 v[48:63], v[112:115], v[134:137], v[48:63]
	v_add_f32_e32 v80, v94, v80
	v_add_f32_e32 v80, v95, v80
	v_cvt_pk_bf16_f32 v132, v92, v93
	v_cvt_pk_bf16_f32 v133, v94, v95
	v_add_f32_e32 v203, v128, v80
	s_mov_b32 m0, s5
	s_nop 0
	global_load_lds_dwordx4 v218, s[98:99]
	s_add_i32 m0, s4, 0x2000
	s_nop 0
	global_load_lds_dwordx4 v219, s[100:101]
	s_waitcnt lgkmcnt(14)
	v_mfma_f32_32x32x16_bf16 v[0:15], v[154:157], v[204:207], v[0:15]
	v_exp_f32_e32 v64, v64
	v_exp_f32_e32 v65, v65
	v_exp_f32_e32 v66, v66
	v_exp_f32_e32 v67, v67
	s_waitcnt lgkmcnt(12)
	v_mfma_f32_32x32x16_bf16 v[16:31], v[154:157], v[96:99], v[16:31]
	v_exp_f32_e32 v68, v68
	v_exp_f32_e32 v69, v69
	v_exp_f32_e32 v70, v70
	v_exp_f32_e32 v71, v71
	ds_read_b128 v[80:83], v200 offset:8192
	ds_read_b128 v[166:169], v200 offset:8704
	s_waitcnt lgkmcnt(12)
	v_mfma_f32_32x32x16_bf16 v[0:15], v[146:149], v[100:103], v[0:15]
	v_exp_f32_e32 v72, v72
	v_exp_f32_e32 v73, v73
	v_exp_f32_e32 v74, v74
	v_exp_f32_e32 v75, v75
	ds_read_b128 v[170:173], v200 offset:10240
	ds_read_b128 v[162:165], v200 offset:10752
	s_waitcnt lgkmcnt(12)
	v_mfma_f32_32x32x16_bf16 v[16:31], v[146:149], v[104:107], v[16:31]
	v_exp_f32_e32 v76, v76
	v_exp_f32_e32 v77, v77
	v_exp_f32_e32 v78, v78
	v_exp_f32_e32 v79, v79
	ds_read_b128 v[124:127], v200 offset:12288
	ds_read_b128 v[120:123], v200 offset:12800
	s_waitcnt lgkmcnt(12)
	v_mfma_f32_32x32x16_bf16 v[0:15], v[138:141], v[108:111], v[0:15]
	v_exp_f32_e32 v48, v48
	v_exp_f32_e32 v49, v49
	v_exp_f32_e32 v50, v50
	v_exp_f32_e32 v51, v51
	ds_read_b128 v[116:119], v200 offset:14336
	ds_read_b128 v[112:115], v200 offset:14848
	s_waitcnt lgkmcnt(12)
	v_mfma_f32_32x32x16_bf16 v[16:31], v[138:141], v[208:211], v[16:31]
	v_exp_f32_e32 v52, v52
	v_exp_f32_e32 v53, v53
	v_exp_f32_e32 v54, v54
	v_exp_f32_e32 v55, v55
	s_waitcnt lgkmcnt(10)
	v_mfma_f32_32x32x16_bf16 v[0:15], v[130:133], v[84:87], v[0:15]
	v_exp_f32_e32 v56, v56
	v_exp_f32_e32 v57, v57
	v_exp_f32_e32 v58, v58
	v_exp_f32_e32 v59, v59
	s_waitcnt lgkmcnt(8)
	v_mfma_f32_32x32x16_bf16 v[16:31], v[130:133], v[88:91], v[16:31]
	v_exp_f32_e32 v60, v60
	v_exp_f32_e32 v61, v61
	v_exp_f32_e32 v62, v62
	v_exp_f32_e32 v63, v63
	s_waitcnt vmcnt(2) lgkmcnt(0)
	s_barrier
	s_add_u32 s98, s98, 0x8000
	s_addc_u32 s99, s99, 0
	s_add_u32 s100, s100, 0x8000
	s_addc_u32 s101, s101, 0
	s_add_i32 s20, s20, 6
	s_cmpk_lg_i32 s20, 0xf5
	s_cbranch_scc1 .Lattn6
